# mixer work queue: first item of every workgroup is static (its block index), shared counter serves items 256.. only
# speedup vs baseline: 1.0052x; 1.0010x over previous
; #define LAS __attribute__((address_space(3)))
; __device__ __forceinline__ int otid() { int t = (int)threadIdx.x; asm volatile("" : "+v"(t)); return t; }
; __device__ __forceinline__ void mix_phase(CA& A0, int l, LAS unsigned char* lds) {
;     const int tid = otid();
;     unsigned* counter = (unsigned*)(A0.ws + WS_CTL) + 64 * l;
;     volatile LAS int* slot = (volatile LAS int*)(lds + LDS_MAIN);
;     float lam_init = 0.8f - 0.6f * expf(-0.3f * (float)l), lam;
;     { const float* lv = A0.diff_lambda + l * 128; float s1 = 0.f, s2 = 0.f;
;       for (int i = 0; i < 32; ++i) { s1 += lv[i] * lv[32 + i]; s2 += lv[64 + i] * lv[96 + i]; }
;       lam = expf(s1) - expf(s2) + lam_init; }
.LBB0_656:
	v_readlane_b32 s6, v237, 63
	v_mov_b32_e32 v1, v179
	v_readlane_b32 s7, v236, 0
	s_load_dwordx2 s[6:7], s[6:7], 0x60
	s_waitcnt lgkmcnt(0)
	s_lshl_b32 s8, s88, 7
	s_lshl_b32 s4, s88, 6
	s_ashr_i32 s9, s8, 31
	s_ashr_i32 s5, s4, 31
	s_lshl_b64 s[8:9], s[8:9], 2
	s_add_u32 s6, s6, s8
	s_addc_u32 s7, s7, s9
	global_load_dwordx4 v[2:5], v0, s[6:7]
	global_load_dwordx4 v[6:9], v0, s[6:7] offset:128
	global_load_dwordx4 v[10:13], v0, s[6:7] offset:256
	global_load_dwordx4 v[14:17], v0, s[6:7] offset:384
	global_load_dwordx4 v[18:21], v0, s[6:7] offset:16
	global_load_dwordx4 v[22:25], v0, s[6:7] offset:144
	global_load_dwordx4 v[26:29], v0, s[6:7] offset:272
	global_load_dwordx4 v[30:33], v0, s[6:7] offset:400
	global_load_dwordx4 v[34:37], v0, s[6:7] offset:32
	global_load_dwordx4 v[38:41], v0, s[6:7] offset:160
	global_load_dwordx4 v[42:45], v0, s[6:7] offset:288
	global_load_dwordx4 v[46:49], v0, s[6:7] offset:416
	global_load_dwordx4 v[50:53], v0, s[6:7] offset:48
	global_load_dwordx4 v[54:57], v0, s[6:7] offset:176
	global_load_dwordx4 v[58:61], v0, s[6:7] offset:304
	global_load_dwordx4 v[62:65], v0, s[6:7] offset:432
	global_load_dwordx4 v[66:69], v0, s[6:7] offset:64
	global_load_dwordx4 v[70:73], v0, s[6:7] offset:192
	global_load_dwordx4 v[74:77], v0, s[6:7] offset:320
	global_load_dwordx4 v[78:81], v0, s[6:7] offset:448
	global_load_dwordx4 v[82:85], v0, s[6:7] offset:80
	global_load_dwordx4 v[86:89], v0, s[6:7] offset:208
	global_load_dwordx4 v[90:93], v0, s[6:7] offset:336
	global_load_dwordx4 v[94:97], v0, s[6:7] offset:464
	global_load_dwordx4 v[98:101], v0, s[6:7] offset:96
	global_load_dwordx4 v[102:105], v0, s[6:7] offset:224
	global_load_dwordx4 v[106:109], v0, s[6:7] offset:352
	global_load_dwordx4 v[110:113], v0, s[6:7] offset:480
	global_load_dwordx4 v[114:117], v0, s[6:7] offset:112
	global_load_dwordx4 v[118:121], v0, s[6:7] offset:240
	global_load_dwordx4 v[122:125], v0, s[6:7] offset:368
	global_load_dwordx4 v[126:129], v0, s[6:7] offset:496
	v_cvt_f32_i32_e32 v130, s88
	s_mov_b32 s6, 0x3fb8aa3b
	s_mov_b32 s7, 0xc2ce8ed0
	s_mov_b32 s8, 0x42b17218
	v_mul_f32_e32 v130, 0xbe99999a, v130
	v_mul_f32_e32 v131, 0x3fb8aa3b, v130
	v_fma_f32 v132, v130, s6, -v131
	v_rndne_f32_e32 v133, v131
	v_fmac_f32_e32 v132, 0x32a5705f, v130
	v_sub_f32_e32 v131, v131, v133
	v_add_f32_e32 v131, v131, v132
	v_cvt_i32_f32_e32 v133, v133
	v_exp_f32_e32 v131, v131
	v_cmp_ngt_f32_e32 vcc, s7, v130
	s_lshl_b64 s[4:5], s[4:5], 2
	v_readlane_b32 s10, v236, 1
	v_ldexp_f32 v131, v131, v133
	v_cndmask_b32_e32 v131, 0, v131, vcc
	v_cmp_nlt_f32_e32 vcc, s8, v130
	v_readlane_b32 s11, v236, 2
	s_add_u32 s4, s10, s4
	v_cndmask_b32_e32 v130, v221, v131, vcc
	s_addc_u32 s5, s11, s5
	v_writelane_b32 v236, s4, 3
	v_cmp_eq_u32_e64 s[12:13], 0, v1
	s_waitcnt vmcnt(0)
	v_fma_f32 v2, v2, v6, 0
	v_fmac_f32_e32 v2, v3, v7
	v_fmac_f32_e32 v2, v4, v8
	v_fmac_f32_e32 v2, v5, v9
	v_fmac_f32_e32 v2, v18, v22
	v_fmac_f32_e32 v2, v19, v23
	v_fmac_f32_e32 v2, v20, v24
	v_fmac_f32_e32 v2, v21, v25
	v_fma_f32 v6, v10, v14, 0
	v_fmac_f32_e32 v2, v34, v38
	v_fmac_f32_e32 v6, v11, v15
	v_fmac_f32_e32 v2, v35, v39
	v_fmac_f32_e32 v6, v12, v16
	v_fmac_f32_e32 v2, v36, v40
	v_fmac_f32_e32 v6, v13, v17
	v_fmac_f32_e32 v2, v37, v41
	v_fmac_f32_e32 v6, v26, v30
	v_fmac_f32_e32 v2, v50, v54
	v_fmac_f32_e32 v6, v27, v31
	v_fmac_f32_e32 v2, v51, v55
	v_fmac_f32_e32 v6, v28, v32
	v_fmac_f32_e32 v2, v52, v56
	v_fmac_f32_e32 v6, v29, v33
	v_fmac_f32_e32 v2, v53, v57
	v_fmac_f32_e32 v6, v42, v46
	v_fmac_f32_e32 v2, v66, v70
	v_fmac_f32_e32 v6, v43, v47
	v_fmac_f32_e32 v2, v67, v71
	v_fmac_f32_e32 v6, v44, v48
	v_fmac_f32_e32 v2, v68, v72
	v_fmac_f32_e32 v6, v45, v49
	v_fmac_f32_e32 v2, v69, v73
	v_fmac_f32_e32 v6, v58, v62
	v_fmac_f32_e32 v2, v82, v86
	v_fmac_f32_e32 v6, v59, v63
	v_fmac_f32_e32 v2, v83, v87
	v_fmac_f32_e32 v6, v60, v64
	v_fmac_f32_e32 v2, v84, v88
	v_fmac_f32_e32 v6, v61, v65
	v_fmac_f32_e32 v2, v85, v89
	v_fmac_f32_e32 v6, v74, v78
	v_fmac_f32_e32 v2, v98, v102
	v_fmac_f32_e32 v6, v75, v79
	v_fmac_f32_e32 v2, v99, v103
	v_fmac_f32_e32 v6, v76, v80
	v_fmac_f32_e32 v2, v100, v104
	v_fmac_f32_e32 v6, v77, v81
	v_fmac_f32_e32 v2, v101, v105
	v_fmac_f32_e32 v6, v90, v94
	v_fmac_f32_e32 v2, v114, v118
	v_fmac_f32_e32 v6, v91, v95
	v_fmac_f32_e32 v2, v115, v119
	v_fmac_f32_e32 v6, v92, v96
	v_fmac_f32_e32 v2, v116, v120
	v_fmac_f32_e32 v6, v93, v97
	v_fmac_f32_e32 v2, v117, v121
	v_fmac_f32_e32 v6, v106, v110
	v_mul_f32_e32 v3, 0x3fb8aa3b, v2
	v_fmac_f32_e32 v6, v107, v111
	v_fma_f32 v4, v2, s6, -v3
	v_rndne_f32_e32 v5, v3
	v_fmac_f32_e32 v6, v108, v112
	v_fmac_f32_e32 v4, 0x32a5705f, v2
	v_sub_f32_e32 v3, v3, v5
	v_fmac_f32_e32 v6, v109, v113
	v_add_f32_e32 v3, v3, v4
	v_fmac_f32_e32 v6, v122, v126
	v_exp_f32_e32 v3, v3
	v_cvt_i32_f32_e32 v4, v5
	v_fmac_f32_e32 v6, v123, v127
	v_fmac_f32_e32 v6, v124, v128
	v_fmac_f32_e32 v6, v125, v129
	v_ldexp_f32 v3, v3, v4
	v_mul_f32_e32 v4, 0x3fb8aa3b, v6
	v_fma_f32 v7, v6, s6, -v4
	v_rndne_f32_e32 v8, v4
	v_fmac_f32_e32 v7, 0x32a5705f, v6
	v_sub_f32_e32 v4, v4, v8
	v_add_f32_e32 v4, v4, v7
	v_exp_f32_e32 v4, v4
	v_cvt_i32_f32_e32 v7, v8
	v_cmp_ngt_f32_e32 vcc, s7, v2
	v_fmamk_f32 v5, v130, 0xbf19999a, v218
	v_writelane_b32 v236, s5, 4
	v_cndmask_b32_e32 v3, 0, v3, vcc
	v_cmp_nlt_f32_e32 vcc, s8, v2
	v_sub_f32_e32 v136, 1.0, v5
	v_writelane_b32 v236, s12, 5
	v_cndmask_b32_e32 v2, v221, v3, vcc
	v_ldexp_f32 v3, v4, v7
	v_cmp_ngt_f32_e32 vcc, s7, v6
	v_writelane_b32 v236, s13, 6
	s_nop 0
	v_cndmask_b32_e32 v3, 0, v3, vcc
	v_cmp_nlt_f32_e32 vcc, s8, v6
	s_nop 1
	v_cndmask_b32_e32 v3, v221, v3, vcc
	v_sub_f32_e32 v2, v2, v3
	v_add_f32_e32 v128, v5, v2
	v_mov_b32_e32 v129, v128
	v_readlane_b32 s6, v237, 62
	s_nop 3
	v_mov_b32_e32 v239, s6
	s_branch .LBB0_660

; __device__ __forceinline__ void mix_phase(CA& A0, int l, LAS unsigned char* lds) {
;     ...
;     for (;;) {
;         __syncthreads();
;         if (tid == 0) *slot = (int)atomicAdd(counter, 1u);
;         __syncthreads();
;         const int it = *slot;
;         if (it >= MIX_ITEMS) break;
.LBB0_660:
	s_barrier
	s_and_saveexec_b64 s[4:5], s[12:13]
	s_cbranch_execz .LBB0_664
	v_readfirstlane_b32 s6, v239
	v_mov_b32_e32 v239, -1
	v_mov_b32_e32 v1, 0
	s_nop 1
	s_cmp_eq_u32 s6, -1
	s_cbranch_scc0 .Lmy_q_have
	s_mov_b64 s[8:9], exec
	v_mbcnt_lo_u32_b32 v1, s8, 0
	v_mbcnt_hi_u32_b32 v1, s9, v1
	v_cmp_eq_u32_e32 vcc, 0, v1
	s_and_saveexec_b64 s[6:7], vcc
	s_cbranch_execz .LBB0_663
	s_bcnt1_i32_b64 s8, s[8:9]
	v_mov_b32_e32 v2, s8
	v_readlane_b32 s8, v236, 3
	v_readlane_b32 s9, v236, 4
	s_nop 4
	global_atomic_add v2, v0, v2, s[8:9] sc0
.LBB0_663:
	s_or_b64 exec, exec, s[6:7]
	s_waitcnt vmcnt(0)
	v_readfirstlane_b32 s6, v2
	s_nop 3
	s_addk_i32 s6, 0x100
	s_nop 1
